# conv: XCD-aware virtual block order so neighbouring grid rows (3x3 halo) are processed on one XCD and reuse its L2
# speedup vs baseline: 1.0002x; 1.0002x over previous
.LBB0_720:
	s_cmp_lt_i32 s56, 5
	s_cselect_b64 s[2:3], -1, 0
	s_and_b64 s[20:21], s[2:3], s[0:1]
	s_andn2_b64 vcc, exec, s[20:21]
	s_and_b32 s98, s72, 7
	s_cmp_lg_u32 s98, 0
	s_mov_b32 s99, s33
	s_cbranch_scc1 .Lconv_vcu_done
	s_lshr_b32 s98, s72, 3
	s_and_b32 s99, s33, 7
	s_mul_i32 s99, s99, s98
	s_lshr_b32 s100, s33, 3
	s_add_i32 s99, s99, s100
.Lconv_vcu_done:
	v_lshl_add_u32 v184, s99, 9, v145
	s_cbranch_vccnz .LBB0_762
	v_lshl_add_u32 v20, s33, 9, v145
	s_mov_b32 s0, 0x20000
	v_cmp_gt_i32_e32 vcc, s0, v20
	s_and_saveexec_b64 s[0:1], vcc
	s_cbranch_execz .LBB0_726
	s_add_u32 s2, s54, 0x5400000
	s_addc_u32 s3, s55, 0
	s_add_u32 s4, s54, 0x5c00000
	s_addc_u32 s5, s55, 0
	s_lshl_b32 s8, s72, 9
	s_mov_b64 s[6:7], 0
	v_mov_b32_e32 v5, 0
	s_mov_b32 s9, 0x1ffff
